# attention tile loop: LDS-DMA loads use scalar base + 32-bit lane offset (seven 64-bit VALU adds per iteration removed), row-max chain heads simplified, two dead moves removed
# speedup vs baseline: 1.0169x; 1.0067x over previous
.LBB0_416:
	v_mov_b32_e32 v1, v198
	s_load_dwordx8 s[4:11], s[0:1], 0x48
	v_and_b32_e32 v0, 63, v1
	v_lshlrev_b32_e32 v2, 2, v0
	s_cmpk_gt_i32 s3, 0x3ff
	s_waitcnt lgkmcnt(0)
	global_load_dword v3, v2, s[4:5]
	global_load_dword v4, v2, s[6:7]
	global_load_dword v5, v2, s[8:9]
	global_load_dword v6, v2, s[10:11]
	v_mbcnt_hi_u32_b32 v2, -1, v178
	v_and_b32_e32 v7, 64, v2
	v_xor_b32_e32 v8, 1, v2
	v_add_u32_e32 v7, 64, v7
	v_cmp_lt_i32_e32 vcc, v8, v7
	v_xor_b32_e32 v9, 2, v2
	v_xor_b32_e32 v10, 4, v2
	v_cndmask_b32_e32 v8, v2, v8, vcc
	v_lshlrev_b32_e32 v199, 2, v8
	v_cmp_lt_i32_e32 vcc, v9, v7
	v_xor_b32_e32 v11, 8, v2
	v_xor_b32_e32 v12, 16, v2
	v_cndmask_b32_e32 v9, v2, v9, vcc
	v_lshlrev_b32_e32 v200, 2, v9
	v_cmp_lt_i32_e32 vcc, v10, v7
	v_xor_b32_e32 v13, 32, v2
	v_readfirstlane_b32 s4, v1
	s_mov_b32 s21, 0
	s_waitcnt vmcnt(2)
	v_mul_f32_e32 v8, v3, v4
	ds_bpermute_b32 v8, v199, v8
	s_waitcnt vmcnt(0)
	v_mul_f32_e32 v14, v5, v6
	ds_bpermute_b32 v14, v199, v14
	s_waitcnt lgkmcnt(1)
	v_fmac_f32_e32 v8, v3, v4
	ds_bpermute_b32 v3, v200, v8
	s_waitcnt lgkmcnt(1)
	v_fmac_f32_e32 v14, v5, v6
	ds_bpermute_b32 v4, v200, v14
	v_cndmask_b32_e32 v5, v2, v10, vcc
	v_lshlrev_b32_e32 v201, 2, v5
	s_waitcnt lgkmcnt(1)
	v_add_f32_e32 v3, v8, v3
	ds_bpermute_b32 v5, v201, v3
	s_waitcnt lgkmcnt(1)
	v_add_f32_e32 v4, v14, v4
	ds_bpermute_b32 v6, v201, v4
	v_cmp_lt_i32_e32 vcc, v11, v7
	s_waitcnt lgkmcnt(1)
	v_add_f32_e32 v3, v3, v5
	v_cndmask_b32_e32 v8, v2, v11, vcc
	v_lshlrev_b32_e32 v202, 2, v8
	s_waitcnt lgkmcnt(0)
	v_add_f32_e32 v4, v4, v6
	ds_bpermute_b32 v5, v202, v3
	ds_bpermute_b32 v6, v202, v4
	v_cmp_lt_i32_e32 vcc, v12, v7
	s_waitcnt lgkmcnt(1)
	v_add_f32_e32 v3, v3, v5
	v_cndmask_b32_e32 v8, v2, v12, vcc
	v_lshlrev_b32_e32 v203, 2, v8
	s_waitcnt lgkmcnt(0)
	v_add_f32_e32 v4, v4, v6
	ds_bpermute_b32 v5, v203, v3
	ds_bpermute_b32 v6, v203, v4
	v_cmp_lt_i32_e32 vcc, v13, v7
	s_nop 1
	v_cndmask_b32_e32 v2, v2, v13, vcc
	v_lshlrev_b32_e32 v204, 2, v2
	s_waitcnt lgkmcnt(1)
	v_add_f32_e32 v2, v3, v5
	s_waitcnt lgkmcnt(0)
	v_add_f32_e32 v3, v4, v6
	ds_bpermute_b32 v4, v204, v2
	ds_bpermute_b32 v5, v204, v3
	s_cbranch_scc1 .LBB0_436
	s_waitcnt lgkmcnt(1)
	v_add_f32_e32 v2, v2, v4
	s_waitcnt lgkmcnt(0)
	v_add_f32_e32 v3, v3, v5
	s_load_dwordx2 s[88:89], s[0:1], 0x68
	v_lshlrev_b32_e32 v250, 4, v198
	v_cmp_gt_u32_e32 vcc, 32, v198
	s_waitcnt lgkmcnt(0)
	s_and_saveexec_b64 s[90:91], vcc
	global_load_dwordx4 v[252:255], v250, s[88:89]
	v_add_u32_e32 v250, 0x1f000, v250
	s_waitcnt vmcnt(0)
	ds_write_b128 v250, v[252:255]
	s_or_b64 exec, exec, s[90:91]
	s_waitcnt lgkmcnt(0)
	s_ashr_i32 s4, s4, 6
	v_mul_f32_e32 v2, 0x3fb8aa3b, v2
	v_mul_f32_e32 v3, 0x3fb8aa3b, v3
	s_lshl_b32 s5, s4, 3
	v_lshrrev_b32_e32 v4, 3, v0
	v_exp_f32_e32 v2, v2
	v_exp_f32_e32 v3, v3
	v_or_b32_e32 v5, s5, v4
	v_lshrrev_b32_e32 v7, 4, v0
	v_lshrrev_b32_e32 v6, 1, v5
	v_or_b32_e32 v8, s5, v7
	v_lshlrev_b32_e32 v7, 2, v7
	v_xor_b32_e32 v6, v6, v1
	v_bitop3_b32 v7, v7, v1, 12 bitop3:0x78
	v_lshlrev_b32_e32 v6, 3, v6
	v_and_or_b32 v7, v1, 3, v7
	v_lshlrev_b32_e32 v8, 10, v8
	v_lshlrev_b32_e32 v5, 10, v5
	v_sub_f32_e32 v2, v2, v3
	v_lshrrev_b32_e32 v3, 5, v0
	v_lshl_or_b32 v176, v7, 3, v8
	v_and_b32_e32 v7, 31, v1
	v_and_or_b32 v180, v6, 56, v5
	v_lshrrev_b32_e32 v6, 1, v1
	v_lshlrev_b32_e32 v5, 7, v7
	v_bfe_u32 v8, v1, 1, 3
	v_bitop3_b32 v6, v3, v6, 7 bitop3:0x78
	v_lshl_or_b32 v206, v6, 4, v5
	v_bitop3_b32 v6, v3, v8, 2 bitop3:0x36
	v_lshl_or_b32 v207, v6, 4, v5
	v_bitop3_b32 v6, v3, v8, 4 bitop3:0x36
	s_lshl_b32 s40, s4, 5
	v_lshl_or_b32 v208, v6, 4, v5
	v_bitop3_b32 v6, v3, v8, 6 bitop3:0x36
	s_lshl_b32 s42, s4, 10
	v_bfe_u32 v1, v1, 2, 2
	s_lshl_b32 s4, s4, 13
	v_lshl_or_b32 v209, v6, 4, v5
	v_and_or_b32 v4, v4, 4, v1
	v_lshlrev_b32_e32 v5, 1, v0
	v_lshlrev_b32_e32 v6, 3, v0
	s_add_i32 s4, s4, 0
	s_add_i32 s43, s42, 0
	v_lshlrev_b32_e32 v4, 8, v4
	v_and_b32_e32 v5, 32, v5
	v_and_b32_e32 v6, 24, v6
	v_lshl_add_u32 v210, v0, 2, s4
	v_lshlrev_b32_e32 v0, 4, v3
	s_add_i32 s4, s43, s42
	v_or3_b32 v4, v4, v5, v6
	v_lshlrev_b32_e32 v5, 6, v1
	v_lshl_or_b32 v0, v7, 11, v0
	v_mov_b32_e32 v1, 0
	s_add_i32 s65, s4, 0x6000
	s_add_i32 s66, s4, 0x6400
	s_add_i32 s67, s4, 0xa000
	s_add_i32 s68, s4, 0xa400
	s_movk_i32 s4, 0x80
	s_ashr_i32 s41, s40, 31
	v_lshl_add_u64 v[182:183], s[58:59], 0, v[0:1]
	v_mov_b32_e32 v181, v1
	s_add_i32 s64, s43, 0x2000
	v_lshl_add_u64 v[184:185], s[62:63], 0, v[0:1]
	v_mov_b32_e32 v177, v1
	v_mov_b32_e32 v179, v1
	v_bitop3_b32 v1, v4, s4, v5 bitop3:0x36
	s_movk_i32 s4, 0xc0
	v_add_f32_e32 v205, 0x3e4ccccd, v2
	v_lshlrev_b32_e32 v2, 3, v3
	v_or_b32_e32 v6, v4, v5
	v_bitop3_b32 v0, v4, 64, v5 bitop3:0x36
	v_bitop3_b32 v3, v4, s4, v5 bitop3:0x36
	s_add_u32 s62, s44, 0x16820000
	v_or_b32_e32 v178, 0x1000, v176
	s_addc_u32 s63, s45, 0
	s_lshl_b32 s69, s3, 4
	s_lshl_b32 s70, s46, 4
	s_mov_b64 s[22:23], 0x20000
	s_movk_i32 s71, 0x4000
	s_mov_b64 s[24:25], 0x60000
	v_mov_b32_e32 v211, 0x358637bd
	s_mov_b32 s72, 0x800000
	v_lshlrev_b32_e32 v212, 2, v2
	v_add_u32_e32 v251, 0x1f000, v212
	v_add_u32_e32 v213, 0, v6
	v_add_u32_e32 v214, 0, v0
	v_add_u32_e32 v215, 0, v1
	v_add_u32_e32 v248, 0, v3
	v_lshlrev_b32_e32 v252, 1, v180
	v_lshlrev_b32_e32 v253, 1, v176
	v_lshlrev_b32_e32 v254, 1, v178
	s_branch .LBB0_419

.LBB0_423:
	v_add_u32_e32 v81, s5, v206
	ds_read_b128 v[82:85], v81
	ds_read_b128 v[86:89], v81 offset:4096
	v_add_u32_e32 v90, s5, v207
	v_add_u32_e32 v94, s5, v208
	v_exp_f32_e32 v128, v128
	v_exp_f32_e32 v129, v129
	v_exp_f32_e32 v152, v96
	v_exp_f32_e32 v153, v97
	v_exp_f32_e32 v108, v108
	v_exp_f32_e32 v109, v109
	v_exp_f32_e32 v110, v110
	v_exp_f32_e32 v111, v111
	v_add_f32_e32 v154, v153, v152
	v_add_u32_e32 v81, s5, v209
	s_waitcnt lgkmcnt(1)
	v_mfma_f32_32x32x16_bf16 v[112:127], v[82:85], v[160:163], v[64:79]
	ds_read_b128 v[82:85], v90
	ds_read_b128 v[90:93], v90 offset:4096
	ds_read_b128 v[144:147], v94
	ds_read_b128 v[148:151], v94 offset:4096
	s_add_i32 s4, s4, 2
	s_waitcnt lgkmcnt(4)
	v_mfma_f32_32x32x16_bf16 v[216:231], v[86:89], v[160:163], v[64:79]
	ds_read_b128 v[86:89], v81
	ds_read_b128 v[94:97], v81 offset:4096
	v_add_f32_e32 v81, v129, v128
	v_add_f32_e32 v81, v154, v81
	v_cvt_pk_bf16_f32 v128, v128, v129
	s_add_i32 s5, s76, s77
	s_cmpk_eq_i32 s5, 0x2000
	s_waitcnt lgkmcnt(5)
	v_mfma_f32_32x32x16_bf16 v[112:127], v[82:85], v[164:167], v[112:127]
	v_exp_f32_e32 v83, v130
	v_exp_f32_e32 v84, v131
	v_exp_f32_e32 v85, v98
	v_exp_f32_e32 v98, v99
	v_exp_f32_e32 v99, v103
	v_cvt_pk_bf16_f32 v129, v83, v84
	v_exp_f32_e32 v103, v137
	s_waitcnt lgkmcnt(4)
	v_mfma_f32_32x32x16_bf16 v[216:231], v[90:93], v[164:167], v[216:231]
	v_add_f32_e32 v90, v84, v83
	v_add_f32_e32 v91, v98, v85
	v_add_f32_e32 v90, v91, v90
	v_add_f32_e32 v81, v90, v81
	v_exp_f32_e32 v90, v132
	v_exp_f32_e32 v91, v133
	v_exp_f32_e32 v92, v100
	v_exp_f32_e32 v93, v101
	s_waitcnt lgkmcnt(3)
	v_mfma_f32_32x32x16_bf16 v[112:127], v[144:147], v[168:171], v[112:127]
	v_cvt_pk_bf16_f32 v83, v85, v98
	v_add_f32_e32 v84, v91, v90
	v_add_f32_e32 v85, v93, v92
	v_add_f32_e32 v84, v85, v84
	v_cvt_pk_bf16_f32 v130, v90, v91
	v_exp_f32_e32 v85, v134
	v_exp_f32_e32 v90, v135
	s_waitcnt lgkmcnt(2)
	v_mfma_f32_32x32x16_bf16 v[216:231], v[148:151], v[168:171], v[216:231]
	v_exp_f32_e32 v98, v102
	v_add_f32_e32 v81, v84, v81
	v_add_f32_e32 v91, v90, v85
	v_exp_f32_e32 v102, v136
	v_exp_f32_e32 v136, v104
	v_exp_f32_e32 v137, v105
	v_cvt_pk_bf16_f32 v84, v92, v93
	s_waitcnt lgkmcnt(1)
	v_mfma_f32_32x32x16_bf16 v[112:127], v[86:89], v[172:175], v[112:127]
	v_add_f32_e32 v86, v99, v98
	v_add_f32_e32 v86, v86, v91
	v_add_f32_e32 v81, v86, v81
	ds_read_b64_tr_b16 v[86:87], v213 offset:40960
	ds_read_b64_tr_b16 v[88:89], v213 offset:43008
	v_cvt_pk_bf16_f32 v131, v85, v90
	v_add_f32_e32 v104, v103, v102
	v_add_f32_e32 v105, v137, v136
	s_waitcnt lgkmcnt(2)
	v_mfma_f32_32x32x16_bf16 v[216:231], v[94:97], v[172:175], v[216:231]
	ds_read_b64_tr_b16 v[90:91], v214 offset:40960
	ds_read_b64_tr_b16 v[92:93], v214 offset:43008
	ds_read_b64_tr_b16 v[94:95], v213 offset:45056
	ds_read_b64_tr_b16 v[96:97], v213 offset:47104
	v_cvt_pk_bf16_f32 v85, v98, v99
	v_cvt_pk_bf16_f32 v82, v152, v153
	s_cselect_b32 s8, s71, 0x2000
	s_cmpk_lg_i32 s5, 0x6000
	s_cselect_b32 s77, s8, 0
	s_add_u32 s38, s38, 0x40000
	s_waitcnt lgkmcnt(2)
	v_mfma_f32_32x32x16_bf16 v[32:47], v[90:93], v[128:131], v[32:47]
	v_add_f32_e32 v90, v105, v104
	v_add_f32_e32 v81, v90, v81
	v_cvt_pk_bf16_f32 v90, v102, v103
	v_exp_f32_e32 v91, v138
	v_exp_f32_e32 v92, v139
	v_exp_f32_e32 v138, v106
	v_exp_f32_e32 v106, v140
	v_mfma_f32_32x32x16_bf16 v[48:63], v[86:89], v[128:131], v[48:63]
	ds_read_b64_tr_b16 v[86:87], v215 offset:40960
	ds_read_b64_tr_b16 v[88:89], v215 offset:43008
	ds_read_b64_tr_b16 v[98:99], v214 offset:45056
	ds_read_b64_tr_b16 v[100:101], v214 offset:47104
	ds_read_b64_tr_b16 v[102:103], v248 offset:40960
	ds_read_b64_tr_b16 v[104:105], v248 offset:43008
	ds_read_b64_tr_b16 v[132:133], v215 offset:45056
	ds_read_b64_tr_b16 v[134:135], v215 offset:47104
	v_exp_f32_e32 v139, v107
	s_addc_u32 s39, s39, 0
	s_add_i32 s75, s75, 0x20000
	s_and_b64 vcc, exec, s[6:7]
	s_waitcnt lgkmcnt(2)
	v_mfma_f32_32x32x16_bf16 v[0:15], v[102:105], v[128:131], v[0:15]
	v_exp_f32_e32 v102, v141
	v_exp_f32_e32 v103, v142
	v_exp_f32_e32 v104, v143
	v_add_f32_e32 v105, v92, v91
	v_cvt_pk_bf16_f32 v91, v91, v92
	v_cvt_pk_bf16_f32 v92, v106, v102
	v_cvt_pk_bf16_f32 v93, v103, v104
	v_mfma_f32_32x32x16_bf16 v[16:31], v[86:89], v[128:131], v[16:31]
	ds_read_b64_tr_b16 v[86:87], v248 offset:45056
	ds_read_b64_tr_b16 v[88:89], v248 offset:47104
	v_mfma_f32_32x32x16_bf16 v[48:63], v[94:97], v[90:93], v[48:63]
	v_add_f32_e32 v94, v139, v138
	v_add_f32_e32 v94, v94, v105
	v_add_f32_e32 v81, v94, v81
	v_add_f32_e32 v94, v102, v106
	v_add_f32_e32 v95, v109, v108
	v_add_f32_e32 v94, v95, v94
	v_add_f32_e32 v81, v94, v81
	v_mfma_f32_32x32x16_bf16 v[32:47], v[98:101], v[90:93], v[32:47]
	v_add_f32_e32 v94, v104, v103
	v_add_f32_e32 v95, v111, v110
	v_add_f32_e32 v94, v95, v94
	v_add_f32_e32 v106, v94, v81
	v_max_f32_e32 v81, v112, v113
	s_waitcnt lgkmcnt(2)
	v_mfma_f32_32x32x16_bf16 v[16:31], v[132:135], v[90:93], v[16:31]
	ds_read_b64_tr_b16 v[94:95], v213 offset:49152
	ds_read_b64_tr_b16 v[96:97], v213 offset:51200
	v_max3_f32 v81, v81, v114, v115
	v_max3_f32 v81, v81, v116, v117
	v_max3_f32 v81, v81, v118, v119
	v_max3_f32 v81, v81, v120, v121
	v_max3_f32 v81, v81, v122, v123
	v_max3_f32 v81, v81, v124, v125
	s_waitcnt lgkmcnt(2)
	v_mfma_f32_32x32x16_bf16 v[0:15], v[86:89], v[90:93], v[0:15]
	ds_read_b64_tr_b16 v[86:87], v214 offset:49152
	ds_read_b64_tr_b16 v[88:89], v214 offset:51200
	ds_read_b64_tr_b16 v[90:91], v213 offset:53248
	ds_read_b64_tr_b16 v[92:93], v213 offset:55296
	v_max3_f32 v81, v81, v126, v127
	v_max3_f32 v81, v81, v216, v217
	v_max3_f32 v81, v81, v218, v219
	v_max3_f32 v81, v81, v220, v221
	v_max3_f32 v81, v81, v222, v223
	v_max3_f32 v81, v81, v224, v225
	s_waitcnt lgkmcnt(4)
	v_mfma_f32_32x32x16_bf16 v[48:63], v[94:97], v[82:85], v[48:63]
	ds_read_b64_tr_b16 v[94:95], v215 offset:49152
	ds_read_b64_tr_b16 v[96:97], v215 offset:51200
	ds_read_b64_tr_b16 v[98:99], v214 offset:53248
	ds_read_b64_tr_b16 v[100:101], v214 offset:55296
	v_max3_f32 v81, v81, v226, v227
	v_max3_f32 v81, v81, v228, v229
	v_max3_f32 v107, v81, v230, v231
	v_add_f32_e32 v196, v194, v106
	v_add_f32_e32 v197, v195, v107
	s_waitcnt lgkmcnt(6)
	v_mfma_f32_32x32x16_bf16 v[32:47], v[86:89], v[82:85], v[32:47]
	ds_read_b64_tr_b16 v[86:87], v248 offset:49152
	ds_read_b64_tr_b16 v[88:89], v248 offset:51200
	ds_read_b64_tr_b16 v[102:103], v215 offset:53248
	ds_read_b64_tr_b16 v[104:105], v215 offset:55296
	s_waitcnt lgkmcnt(6)
	v_mfma_f32_32x32x16_bf16 v[16:31], v[94:97], v[82:85], v[16:31]
	ds_read_b64_tr_b16 v[94:95], v248 offset:53248
	ds_read_b64_tr_b16 v[96:97], v248 offset:55296
	s_waitcnt vmcnt(0)
	s_waitcnt lgkmcnt(4)
	v_mfma_f32_32x32x16_bf16 v[0:15], v[86:89], v[82:85], v[0:15]
	v_cvt_pk_bf16_f32 v85, v110, v111
	v_cvt_pk_bf16_f32 v84, v108, v109
	v_cvt_pk_bf16_f32 v83, v138, v139
	v_cvt_pk_bf16_f32 v82, v136, v137
	s_nop 1
	v_mfma_f32_32x32x16_bf16 v[48:63], v[90:93], v[82:85], v[48:63]
	s_waitcnt lgkmcnt(0)
	s_barrier
	v_mfma_f32_32x32x16_bf16 v[32:47], v[98:101], v[82:85], v[32:47]
	s_cmp_gt_u32 s4, 33
	s_cselect_b64 s[6:7], -1, 0
	s_cmp_lt_u32 s4, 34
	s_cselect_b32 s20, s75, 0x230000
	v_mfma_f32_32x32x16_bf16 v[16:31], v[102:105], v[82:85], v[16:31]
	s_lshl_b64 s[8:9], s[20:21], 1
	s_add_u32 s8, s36, s8
	s_addc_u32 s9, s37, s9
	s_add_i32 s5, s77, 0
	v_mfma_f32_32x32x16_bf16 v[0:15], v[94:97], v[82:85], v[0:15]
	s_cbranch_vccnz .LBB0_432
.LBB0_424:
	v_add_u32_e32 v86, s76, v206
	ds_read_b128 v[82:85], v86
	ds_read_b128 v[86:89], v86 offset:4096
	s_add_i32 m0, s5, s42
	s_nop 0
	global_load_lds_dwordx4 v252, s[8:9]
	s_mov_b32 m0, s67
	s_nop 0
	global_load_lds_dwordx4 v253, s[38:39]
	s_mov_b32 m0, s68
	s_nop 0
	global_load_lds_dwordx4 v254, s[38:39]
	v_add_f32_e32 v81, 0x41000000, v195
	v_cmp_gt_f32_e32 vcc, v197, v81
	s_cbranch_vccz .LBB0_428
	s_waitcnt lgkmcnt(0)
	ds_bpermute_b32 v80, v204, v197
	v_max_f32_e32 v82, v197, v197
	s_waitcnt lgkmcnt(0)
	v_max_f32_e32 v80, v80, v80
	v_max_f32_e32 v80, v82, v80
	v_mov_b64_e32 v[96:97], v[78:79]
	v_cmp_gt_f32_e32 vcc, v80, v81
	v_mov_b64_e32 v[94:95], v[76:77]
	v_mov_b64_e32 v[92:93], v[74:75]
	v_mov_b64_e32 v[90:91], v[72:73]
	v_mov_b64_e32 v[88:89], v[70:71]
	v_mov_b64_e32 v[86:87], v[68:69]
	v_mov_b64_e32 v[84:85], v[66:67]
	v_mov_b64_e32 v[82:83], v[64:65]
	s_and_saveexec_b64 s[8:9], vcc
	s_cbranch_execz .LBB0_427
	v_sub_f32_e32 v65, v80, v195
	v_exp_f32_e64 v64, -v65
	v_xor_b32_e32 v82, 0x80000000, v80
	v_sub_f32_e32 v127, v127, v65
	v_sub_f32_e32 v126, v126, v65
	v_mul_f32_e32 v196, v196, v64
	v_pk_mul_f32 v[62:63], v[62:63], v[64:65] op_sel_hi:[1,0]
	v_pk_mul_f32 v[60:61], v[60:61], v[64:65] op_sel_hi:[1,0]
	v_pk_mul_f32 v[58:59], v[58:59], v[64:65] op_sel_hi:[1,0]
	v_pk_mul_f32 v[56:57], v[56:57], v[64:65] op_sel_hi:[1,0]
	v_pk_mul_f32 v[54:55], v[54:55], v[64:65] op_sel_hi:[1,0]
	v_pk_mul_f32 v[52:53], v[52:53], v[64:65] op_sel_hi:[1,0]
	v_pk_mul_f32 v[50:51], v[50:51], v[64:65] op_sel_hi:[1,0]
	v_pk_mul_f32 v[48:49], v[48:49], v[64:65] op_sel_hi:[1,0]
	v_pk_mul_f32 v[46:47], v[46:47], v[64:65] op_sel_hi:[1,0]
	v_pk_mul_f32 v[44:45], v[44:45], v[64:65] op_sel_hi:[1,0]
	v_pk_mul_f32 v[42:43], v[42:43], v[64:65] op_sel_hi:[1,0]
	v_pk_mul_f32 v[40:41], v[40:41], v[64:65] op_sel_hi:[1,0]
	v_pk_mul_f32 v[38:39], v[38:39], v[64:65] op_sel_hi:[1,0]
	v_pk_mul_f32 v[36:37], v[36:37], v[64:65] op_sel_hi:[1,0]
	v_pk_mul_f32 v[34:35], v[34:35], v[64:65] op_sel_hi:[1,0]
	v_pk_mul_f32 v[32:33], v[32:33], v[64:65] op_sel_hi:[1,0]
	v_pk_mul_f32 v[30:31], v[30:31], v[64:65] op_sel_hi:[1,0]
	v_pk_mul_f32 v[28:29], v[28:29], v[64:65] op_sel_hi:[1,0]
	v_pk_mul_f32 v[26:27], v[26:27], v[64:65] op_sel_hi:[1,0]
	v_pk_mul_f32 v[24:25], v[24:25], v[64:65] op_sel_hi:[1,0]
	v_pk_mul_f32 v[22:23], v[22:23], v[64:65] op_sel_hi:[1,0]
	v_pk_mul_f32 v[20:21], v[20:21], v[64:65] op_sel_hi:[1,0]
	v_pk_mul_f32 v[18:19], v[18:19], v[64:65] op_sel_hi:[1,0]
	v_pk_mul_f32 v[16:17], v[16:17], v[64:65] op_sel_hi:[1,0]
	v_pk_mul_f32 v[14:15], v[14:15], v[64:65] op_sel_hi:[1,0]
	v_pk_mul_f32 v[12:13], v[12:13], v[64:65] op_sel_hi:[1,0]
	v_pk_mul_f32 v[10:11], v[10:11], v[64:65] op_sel_hi:[1,0]
	v_pk_mul_f32 v[8:9], v[8:9], v[64:65] op_sel_hi:[1,0]
	v_pk_mul_f32 v[6:7], v[6:7], v[64:65] op_sel_hi:[1,0]
	v_pk_mul_f32 v[4:5], v[4:5], v[64:65] op_sel_hi:[1,0]
	v_pk_mul_f32 v[2:3], v[2:3], v[64:65] op_sel_hi:[1,0]
	v_pk_mul_f32 v[0:1], v[0:1], v[64:65] op_sel_hi:[1,0]
	v_sub_f32_e32 v125, v125, v65
	v_sub_f32_e32 v124, v124, v65
	v_sub_f32_e32 v123, v123, v65
	v_sub_f32_e32 v122, v122, v65
	v_sub_f32_e32 v121, v121, v65
	v_sub_f32_e32 v120, v120, v65
	v_sub_f32_e32 v119, v119, v65
	v_sub_f32_e32 v118, v118, v65
	v_sub_f32_e32 v117, v117, v65
	v_sub_f32_e32 v116, v116, v65
	v_sub_f32_e32 v115, v115, v65
	v_sub_f32_e32 v114, v114, v65
	v_sub_f32_e32 v113, v113, v65
	v_sub_f32_e32 v112, v112, v65
	v_sub_f32_e32 v231, v231, v65
	v_sub_f32_e32 v230, v230, v65
	v_sub_f32_e32 v229, v229, v65
	v_sub_f32_e32 v228, v228, v65
	v_sub_f32_e32 v227, v227, v65
	v_sub_f32_e32 v226, v226, v65
	v_sub_f32_e32 v225, v225, v65
	v_sub_f32_e32 v224, v224, v65
	v_sub_f32_e32 v223, v223, v65
	v_sub_f32_e32 v222, v222, v65
	v_sub_f32_e32 v221, v221, v65
	v_sub_f32_e32 v220, v220, v65
	v_sub_f32_e32 v219, v219, v65
	v_sub_f32_e32 v218, v218, v65
	v_sub_f32_e32 v217, v217, v65
	v_sub_f32_e32 v216, v216, v65
	v_add_f32_e32 v81, 0x41000000, v80
	v_mov_b32_e32 v83, v82
	v_mov_b32_e32 v84, v82
	v_mov_b32_e32 v85, v82
	v_mov_b32_e32 v86, v82
	v_mov_b32_e32 v87, v82
	v_mov_b32_e32 v88, v82
	v_mov_b32_e32 v89, v82
	v_mov_b32_e32 v90, v82
	v_mov_b32_e32 v91, v82
	v_mov_b32_e32 v92, v82
	v_mov_b32_e32 v93, v82
	v_mov_b32_e32 v94, v82
	v_mov_b32_e32 v95, v82
	v_mov_b32_e32 v96, v82
	v_mov_b32_e32 v97, v82
	v_mov_b32_e32 v79, v82
	v_mov_b32_e32 v78, v82
	v_mov_b32_e32 v77, v82
	v_mov_b32_e32 v76, v82
	v_mov_b32_e32 v75, v82
	v_mov_b32_e32 v74, v82
	v_mov_b32_e32 v73, v82
	v_mov_b32_e32 v72, v82
	v_mov_b32_e32 v71, v82
	v_mov_b32_e32 v70, v82
	v_mov_b32_e32 v69, v82
	v_mov_b32_e32 v68, v82
	v_mov_b32_e32 v67, v82
	v_mov_b32_e32 v66, v82
	v_mov_b32_e32 v65, v82
	v_mov_b32_e32 v64, v82
	v_mov_b32_e32 v195, v80
.LBB0_427:
	s_or_b64 exec, exec, s[8:9]
	v_mov_b64_e32 v[64:65], v[82:83]
	v_mov_b64_e32 v[66:67], v[84:85]
	v_mov_b64_e32 v[68:69], v[86:87]
	v_mov_b64_e32 v[70:71], v[88:89]
	v_mov_b64_e32 v[72:73], v[90:91]
	v_mov_b64_e32 v[74:75], v[92:93]
	v_mov_b64_e32 v[76:77], v[94:95]
	v_mov_b64_e32 v[78:79], v[96:97]
	v_add_u32_e32 v86, s76, v206
	ds_read_b128 v[82:85], v86
	ds_read_b128 v[86:89], v86 offset:4096
	s_branch .LBB0_429
.LBB0_428:
.LBB0_429:
	s_add_i32 s8, s76, 0
	v_add_u32_e32 v90, s8, v207
	v_add_u32_e32 v94, s8, v208
	v_add_u32_e32 v194, s8, v209
	s_waitcnt lgkmcnt(1)
	v_mfma_f32_32x32x16_bf16 v[128:143], v[82:85], v[160:163], v[64:79]
	ds_read_b128 v[82:85], v90
	ds_read_b128 v[90:93], v90 offset:4096
	v_exp_f32_e32 v95, v112
	v_exp_f32_e32 v245, v113
	v_exp_f32_e32 v145, v217
	v_exp_f32_e32 v244, v115
	v_exp_f32_e32 v115, v221
	v_cvt_pk_bf16_f32 v112, v95, v245
	s_waitcnt lgkmcnt(2)
	v_mfma_f32_32x32x16_bf16 v[96:111], v[86:89], v[160:163], v[64:79]
	ds_read_b128 v[86:89], v94
	ds_read_b128 v[232:235], v94 offset:4096
	ds_read_b128 v[236:239], v194
	ds_read_b128 v[240:243], v194 offset:4096
	v_exp_f32_e32 v94, v114
	v_exp_f32_e32 v114, v117
	v_exp_f32_e32 v156, v228
	s_add_i32 s8, s77, s76
	v_cvt_pk_bf16_f32 v113, v94, v244
	s_cmpk_eq_i32 s8, 0x2000
	s_waitcnt lgkmcnt(5)
	v_mfma_f32_32x32x16_bf16 v[128:143], v[82:85], v[164:167], v[128:143]
	v_exp_f32_e32 v85, v216
	v_exp_f32_e32 v84, v218
	v_exp_f32_e32 v144, v219
	s_cselect_b32 s9, s71, 0x2000
	v_cvt_pk_bf16_f32 v82, v85, v145
	s_cmpk_lg_i32 s8, 0x6000
	s_cselect_b32 s76, s9, 0
	s_waitcnt lgkmcnt(4)
	v_mfma_f32_32x32x16_bf16 v[96:111], v[90:93], v[164:167], v[96:111]
	v_add_f32_e32 v90, v94, v244
	v_add_f32_e32 v91, v95, v245
	v_add_f32_e32 v92, v84, v144
	v_add_f32_e32 v93, v85, v145
	v_exp_f32_e32 v94, v120
	v_add_f32_e32 v90, v90, v92
	v_add_f32_e32 v91, v91, v93
	v_exp_f32_e32 v92, v116
	v_exp_f32_e32 v93, v220
	s_waitcnt lgkmcnt(3)
	v_mfma_f32_32x32x16_bf16 v[128:143], v[86:89], v[168:171], v[128:143]
	v_add_f32_e32 v87, v90, v91
	v_cvt_pk_bf16_f32 v83, v84, v144
	v_add_f32_e32 v84, v92, v114
	v_add_f32_e32 v85, v93, v115
	v_exp_f32_e32 v86, v119
	v_add_f32_e32 v89, v84, v85
	v_exp_f32_e32 v85, v118
	v_exp_f32_e32 v88, v222
	v_exp_f32_e32 v90, v223
	s_waitcnt lgkmcnt(2)
	v_mfma_f32_32x32x16_bf16 v[96:111], v[232:235], v[168:171], v[96:111]
	v_cvt_pk_bf16_f32 v114, v92, v114
	v_cvt_pk_bf16_f32 v84, v93, v115
	v_add_f32_e32 v95, v85, v86
	v_add_f32_e32 v233, v88, v90
	v_cvt_pk_bf16_f32 v115, v85, v86
	v_cvt_pk_bf16_f32 v85, v88, v90
	ds_read_b64_tr_b16 v[90:91], v213 offset:24576
	ds_read_b64_tr_b16 v[92:93], v213 offset:26624
	v_exp_f32_e32 v232, v121
	v_exp_f32_e32 v88, v224
	v_exp_f32_e32 v86, v225
	ds_read_b64_tr_b16 v[116:117], v214 offset:24576
	ds_read_b64_tr_b16 v[118:119], v214 offset:26624
	ds_read_b64_tr_b16 v[144:145], v213 offset:28672
	ds_read_b64_tr_b16 v[146:147], v213 offset:30720
	v_add_f32_e32 v120, v94, v232
	v_add_f32_e32 v121, v95, v233
	s_waitcnt lgkmcnt(4)
	v_mfma_f32_32x32x16_bf16 v[48:63], v[90:93], v[112:115], v[48:63]
	v_add_f32_e32 v90, v88, v86
	v_add_f32_e32 v91, v89, v87
	v_exp_f32_e32 v234, v122
	v_add_f32_e32 v152, v120, v90
	v_add_f32_e32 v153, v121, v91
	ds_read_b64_tr_b16 v[90:91], v215 offset:24576
	ds_read_b64_tr_b16 v[92:93], v215 offset:26624
	ds_read_b64_tr_b16 v[148:149], v214 offset:28672
	ds_read_b64_tr_b16 v[150:151], v214 offset:30720
	v_exp_f32_e32 v235, v226
	v_exp_f32_e32 v87, v124
	v_exp_f32_e32 v89, v125
	v_mfma_f32_32x32x16_bf16 v[128:143], v[236:239], v[172:175], v[128:143]
	v_exp_f32_e32 v236, v123
	v_exp_f32_e32 v237, v227
	v_add_f32_e32 v239, v152, v153
	v_exp_f32_e32 v238, v231
	s_min_u32 s8, s4, 32
	s_min_u32 s10, s4, 33
	s_lshl_b32 s8, s8, 17
	s_waitcnt lgkmcnt(6)
	v_mfma_f32_32x32x16_bf16 v[32:47], v[116:119], v[112:115], v[32:47]
	ds_read_b64_tr_b16 v[116:117], v248 offset:24576
	ds_read_b64_tr_b16 v[118:119], v248 offset:26624
	ds_read_b64_tr_b16 v[120:121], v215 offset:28672
	ds_read_b64_tr_b16 v[122:123], v215 offset:30720
	ds_read_b64_tr_b16 v[152:153], v248 offset:28672
	ds_read_b64_tr_b16 v[154:155], v248 offset:30720
	s_add_u32 s8, s36, s8
	s_addc_u32 s9, s37, 0
	s_waitcnt lgkmcnt(8)
	v_mfma_f32_32x32x16_bf16 v[16:31], v[90:93], v[112:115], v[16:31]
	v_add_f32_e32 v92, v234, v236
	v_add_f32_e32 v93, v235, v237
	v_cvt_pk_bf16_f32 v90, v94, v232
	v_add_f32_e32 v95, v92, v93
	v_cvt_pk_bf16_f32 v91, v234, v236
	v_cvt_pk_bf16_f32 v92, v87, v89
	v_exp_f32_e32 v94, v230
	s_waitcnt lgkmcnt(4)
	v_mfma_f32_32x32x16_bf16 v[0:15], v[116:119], v[112:115], v[0:15]
	v_exp_f32_e32 v112, v126
	v_exp_f32_e32 v114, v127
	v_add_f32_e32 v113, v87, v89
	v_cvt_pk_bf16_f32 v93, v112, v114
	s_nop 1
	v_mfma_f32_32x32x16_bf16 v[48:63], v[144:147], v[90:93], v[48:63]
	v_exp_f32_e32 v144, v229
	v_cvt_pk_bf16_f32 v147, v94, v238
	v_cvt_pk_bf16_f32 v145, v235, v237
	v_add_f32_e32 v115, v156, v144
	v_add_f32_e32 v112, v112, v114
	v_add_f32_e32 v113, v113, v115
	v_add_f32_e32 v114, v94, v238
	v_add_f32_e32 v115, v95, v239
	v_mfma_f32_32x32x16_bf16 v[32:47], v[148:151], v[90:93], v[32:47]
	v_add_f32_e32 v112, v112, v114
	v_add_f32_e32 v113, v113, v115
	v_cvt_pk_bf16_f32 v146, v156, v144
	v_add_f32_e32 v87, v112, v113
	ds_read_b64_tr_b16 v[112:113], v213 offset:32768
	ds_read_b64_tr_b16 v[114:115], v213 offset:34816
	v_add_f32_e32 v194, v196, v87
	v_max_f32_e32 v87, v128, v129
	s_waitcnt lgkmcnt(4)
	v_mfma_f32_32x32x16_bf16 v[16:31], v[120:123], v[90:93], v[16:31]
	v_max3_f32 v87, v87, v130, v131
	v_max3_f32 v87, v87, v132, v133
	v_max3_f32 v87, v87, v134, v135
	v_max3_f32 v87, v87, v136, v137
	v_max3_f32 v87, v87, v138, v139
	v_max3_f32 v87, v87, v140, v141
	v_max3_f32 v87, v87, v142, v143
	s_waitcnt lgkmcnt(2)
	v_mfma_f32_32x32x16_bf16 v[0:15], v[152:155], v[90:93], v[0:15]
	ds_read_b64_tr_b16 v[90:91], v214 offset:32768
	ds_read_b64_tr_b16 v[92:93], v214 offset:34816
	ds_read_b64_tr_b16 v[116:117], v213 offset:36864
	ds_read_b64_tr_b16 v[118:119], v213 offset:38912
	v_cvt_pk_bf16_f32 v144, v88, v86
	s_waitcnt lgkmcnt(4)
	v_mfma_f32_32x32x16_bf16 v[48:63], v[112:115], v[82:85], v[48:63]
	ds_read_b64_tr_b16 v[112:113], v215 offset:32768
	ds_read_b64_tr_b16 v[114:115], v215 offset:34816
	ds_read_b64_tr_b16 v[120:121], v214 offset:36864
	ds_read_b64_tr_b16 v[122:123], v214 offset:38912
	s_waitcnt lgkmcnt(6)
	v_mfma_f32_32x32x16_bf16 v[32:47], v[90:93], v[82:85], v[32:47]
	ds_read_b64_tr_b16 v[90:91], v248 offset:32768
	ds_read_b64_tr_b16 v[92:93], v248 offset:34816
	ds_read_b64_tr_b16 v[124:125], v215 offset:36864
	ds_read_b64_tr_b16 v[126:127], v215 offset:38912
	v_mfma_f32_32x32x16_bf16 v[96:111], v[240:243], v[172:175], v[96:111]
	s_waitcnt lgkmcnt(6)
	v_mfma_f32_32x32x16_bf16 v[16:31], v[112:115], v[82:85], v[16:31]
	ds_read_b64_tr_b16 v[112:113], v248 offset:36864
	ds_read_b64_tr_b16 v[114:115], v248 offset:38912
	s_nop 7
	v_max3_f32 v87, v87, v96, v97
	v_max3_f32 v87, v87, v98, v99
	s_waitcnt vmcnt(0)
	s_waitcnt lgkmcnt(0)
	s_barrier
	v_mfma_f32_32x32x16_bf16 v[0:15], v[90:93], v[82:85], v[0:15]
	s_add_u32 s96, s8, s24
	s_addc_u32 s97, s9, s25
	s_add_i32 m0, s43, s76
	s_nop 0
	global_load_lds_dwordx4 v252, s[96:97]
	s_lshl_b32 s8, s10, 17
	v_max3_f32 v87, v87, v100, v101
	s_add_u32 s8, s26, s8
	v_mfma_f32_32x32x16_bf16 v[48:63], v[116:119], v[144:147], v[48:63]
	v_max3_f32 v87, v87, v102, v103
	s_addc_u32 s9, s27, 0
	v_max3_f32 v87, v87, v104, v105
	s_add_u32 s8, s8, 0x40000
	v_max3_f32 v87, v87, v106, v107
	s_addc_u32 s9, s9, 0
	v_max3_f32 v87, v87, v108, v109
	v_mfma_f32_32x32x16_bf16 v[32:47], v[120:123], v[144:147], v[32:47]
	s_mov_b32 m0, s65
	s_nop 0
	global_load_lds_dwordx4 v253, s[8:9]
	v_max3_f32 v87, v87, v110, v111
	s_mov_b32 m0, s66
	s_nop 0
	global_load_lds_dwordx4 v254, s[8:9]
	v_add_f32_e32 v87, v195, v87
	v_cmp_gt_f32_e32 vcc, v87, v81
	v_mfma_f32_32x32x16_bf16 v[16:31], v[124:127], v[144:147], v[16:31]
	v_mfma_f32_32x32x16_bf16 v[0:15], v[112:115], v[144:147], v[0:15]
	s_cbranch_vccz .LBB0_423
	ds_bpermute_b32 v82, v204, v87
	v_max_f32_e32 v83, v87, v87
	s_waitcnt lgkmcnt(0)
	v_max_f32_e32 v82, v82, v82
	v_max_f32_e32 v112, v83, v82
	v_cmp_gt_f32_e32 vcc, v112, v81
	s_and_saveexec_b64 s[8:9], vcc
	s_cbranch_execz .LBB0_422
	v_sub_f32_e32 v65, v112, v195
	v_exp_f32_e64 v64, -v65
	v_xor_b32_e32 v80, 0x80000000, v112
	v_mov_b32_e32 v81, v80
	v_sub_f32_e32 v128, v128, v65
	v_mul_f32_e32 v194, v194, v64
	v_pk_mul_f32 v[62:63], v[62:63], v[64:65] op_sel_hi:[1,0]
	v_pk_mul_f32 v[60:61], v[60:61], v[64:65] op_sel_hi:[1,0]
	v_pk_mul_f32 v[58:59], v[58:59], v[64:65] op_sel_hi:[1,0]
	v_pk_mul_f32 v[56:57], v[56:57], v[64:65] op_sel_hi:[1,0]
	v_pk_mul_f32 v[54:55], v[54:55], v[64:65] op_sel_hi:[1,0]
	v_pk_mul_f32 v[52:53], v[52:53], v[64:65] op_sel_hi:[1,0]
	v_pk_mul_f32 v[50:51], v[50:51], v[64:65] op_sel_hi:[1,0]
	v_pk_mul_f32 v[48:49], v[48:49], v[64:65] op_sel_hi:[1,0]
	v_pk_mul_f32 v[46:47], v[46:47], v[64:65] op_sel_hi:[1,0]
	v_pk_mul_f32 v[44:45], v[44:45], v[64:65] op_sel_hi:[1,0]
	v_pk_mul_f32 v[42:43], v[42:43], v[64:65] op_sel_hi:[1,0]
	v_pk_mul_f32 v[40:41], v[40:41], v[64:65] op_sel_hi:[1,0]
	v_pk_mul_f32 v[38:39], v[38:39], v[64:65] op_sel_hi:[1,0]
	v_pk_mul_f32 v[36:37], v[36:37], v[64:65] op_sel_hi:[1,0]
	v_pk_mul_f32 v[34:35], v[34:35], v[64:65] op_sel_hi:[1,0]
	v_pk_mul_f32 v[32:33], v[32:33], v[64:65] op_sel_hi:[1,0]
	v_pk_mul_f32 v[30:31], v[30:31], v[64:65] op_sel_hi:[1,0]
	v_pk_mul_f32 v[28:29], v[28:29], v[64:65] op_sel_hi:[1,0]
	v_pk_mul_f32 v[26:27], v[26:27], v[64:65] op_sel_hi:[1,0]
	v_pk_mul_f32 v[24:25], v[24:25], v[64:65] op_sel_hi:[1,0]
	v_pk_mul_f32 v[22:23], v[22:23], v[64:65] op_sel_hi:[1,0]
	v_pk_mul_f32 v[20:21], v[20:21], v[64:65] op_sel_hi:[1,0]
	v_pk_mul_f32 v[18:19], v[18:19], v[64:65] op_sel_hi:[1,0]
	v_pk_mul_f32 v[16:17], v[16:17], v[64:65] op_sel_hi:[1,0]
	v_pk_mul_f32 v[14:15], v[14:15], v[64:65] op_sel_hi:[1,0]
	v_pk_mul_f32 v[12:13], v[12:13], v[64:65] op_sel_hi:[1,0]
	v_pk_mul_f32 v[10:11], v[10:11], v[64:65] op_sel_hi:[1,0]
	v_pk_mul_f32 v[8:9], v[8:9], v[64:65] op_sel_hi:[1,0]
	v_pk_mul_f32 v[6:7], v[6:7], v[64:65] op_sel_hi:[1,0]
	v_pk_mul_f32 v[4:5], v[4:5], v[64:65] op_sel_hi:[1,0]
	v_pk_mul_f32 v[2:3], v[2:3], v[64:65] op_sel_hi:[1,0]
	v_pk_mul_f32 v[0:1], v[0:1], v[64:65] op_sel_hi:[1,0]
	v_sub_f32_e32 v129, v129, v65
	v_sub_f32_e32 v130, v130, v65
	v_sub_f32_e32 v131, v131, v65
	v_sub_f32_e32 v132, v132, v65
	v_sub_f32_e32 v133, v133, v65
	v_sub_f32_e32 v134, v134, v65
	v_sub_f32_e32 v135, v135, v65
	v_sub_f32_e32 v136, v136, v65
	v_sub_f32_e32 v137, v137, v65
	v_sub_f32_e32 v138, v138, v65
	v_sub_f32_e32 v139, v139, v65
	v_sub_f32_e32 v140, v140, v65
	v_sub_f32_e32 v141, v141, v65
	v_sub_f32_e32 v142, v142, v65
	v_sub_f32_e32 v143, v143, v65
	v_sub_f32_e32 v96, v96, v65
	v_sub_f32_e32 v97, v97, v65
	v_sub_f32_e32 v98, v98, v65
	v_sub_f32_e32 v99, v99, v65
	v_sub_f32_e32 v100, v100, v65
	v_sub_f32_e32 v101, v101, v65
	v_sub_f32_e32 v102, v102, v65
	v_sub_f32_e32 v103, v103, v65
	v_sub_f32_e32 v104, v104, v65
	v_sub_f32_e32 v105, v105, v65
	v_sub_f32_e32 v106, v106, v65
	v_sub_f32_e32 v107, v107, v65
	v_sub_f32_e32 v108, v108, v65
	v_sub_f32_e32 v109, v109, v65
	v_sub_f32_e32 v110, v110, v65
	v_sub_f32_e32 v111, v111, v65
	v_mov_b32_e32 v82, v80
	v_mov_b32_e32 v83, v80
	v_mov_b32_e32 v84, v80
	v_mov_b32_e32 v85, v80
	v_mov_b32_e32 v86, v80
	v_mov_b32_e32 v87, v80
	v_mov_b32_e32 v88, v80
	v_mov_b32_e32 v89, v80
	v_mov_b32_e32 v90, v80
	v_mov_b32_e32 v91, v80
	v_mov_b32_e32 v92, v80
	v_mov_b32_e32 v93, v80
	v_mov_b32_e32 v94, v80
	v_mov_b32_e32 v95, v80
	v_mov_b64_e32 v[64:65], v[80:81]
	v_mov_b32_e32 v195, v112
	v_mov_b64_e32 v[66:67], v[82:83]
	v_mov_b64_e32 v[68:69], v[84:85]
	v_mov_b64_e32 v[70:71], v[86:87]
	v_mov_b64_e32 v[72:73], v[88:89]
	v_mov_b64_e32 v[74:75], v[90:91]
	v_mov_b64_e32 v[76:77], v[92:93]
	v_mov_b64_e32 v[78:79], v[94:95]
	s_branch .LBB0_422
